# flag-based single-rendezvous group barriers (co-location decided once at seam 0)
# speedup vs baseline: 1.0308x; 1.0061x over previous
; #define LAS __attribute__((address_space(3)))
; __device__ __forceinline__ unsigned xb_ld(unsigned* p) { return __hip_atomic_load(p, __ATOMIC_RELAXED, __HIP_MEMORY_SCOPE_AGENT); }
; __device__ __forceinline__ unsigned xb_add(unsigned* p, unsigned v) { return __hip_atomic_fetch_add(p, v, __ATOMIC_RELAXED, __HIP_MEMORY_SCOPE_AGENT); }
; __device__ __forceinline__ unsigned xb_xcc_id() { return (unsigned)__builtin_amdgcn_s_getreg((3 << 11) | 20) & 0xFu; }
; __device__ __forceinline__ void grid_barrier(unsigned* barw, int k, volatile LAS unsigned* st) {
;     asm volatile("s_waitcnt vmcnt(0)" ::: "memory");
;     __syncthreads();
;     if (threadIdx.x == 0) {
;         __builtin_amdgcn_s_waitcnt(0);
;         const unsigned x = xb_xcc_id();
;         unsigned nloc = st[0], nx = st[1];
;         if (nloc == 0u) {
;             const unsigned G = gridDim.x;
;             for (;;) { unsigned sum = 0u, cnt = 0u, mine = 0u;
; #pragma unroll
;                 for (unsigned j = 0; j < 16; ++j) { const unsigned c = xb_ld(barw + 64 * j); sum += c; cnt += (c > 0u) ? 1u : 0u; mine = (j == x) ? c : mine; }
;                 if (sum == G) { nloc = mine; nx = cnt; break; }
;                 __builtin_amdgcn_s_sleep(1); }
;             st[0] = nloc; st[1] = nx;
;         }
;         unsigned* sb = barw + 1024 + k * 2304;
;         const unsigned old = xb_add(sb + 64 * x, 1u);
;         if (old + 1u == nloc) {
;             __builtin_amdgcn_fence(__ATOMIC_RELEASE, "agent");
;             asm volatile("s_waitcnt vmcnt(0)" ::: "memory");
;             const unsigned og = xb_add(sb + 2048, 1u);
;             if (og + 1u == nx) xb_add(sb + 2112, 1u);
;             else while (xb_ld(sb + 2112) == 0u) __builtin_amdgcn_s_sleep(1);
;             __builtin_amdgcn_fence(__ATOMIC_ACQUIRE, "agent");
;             xb_add(sb + 1024 + 64 * x, 1u);
;             asm volatile("s_waitcnt vmcnt(0)" ::: "memory");
;         } else {
;             while (xb_ld(sb + 1024 + 64 * x) == 0u) __builtin_amdgcn_s_sleep(1);
;             __builtin_amdgcn_fence(__ATOMIC_ACQUIRE, "agent");
;             asm volatile("s_waitcnt vmcnt(0)" ::: "memory");
;         }
;     }
;     __syncthreads();
; }
.LBB0_680:
	v_readlane_b32 s0, v254, 0
	v_readlane_b32 s1, v254, 1
	s_cmp_gt_i32 s1, 4
	s_cselect_b64 s[72:73], -1, 0
	s_and_b64 s[0:1], s[8:9], s[72:73]
	s_andn2_b64 vcc, exec, s[0:1]
	s_cbranch_vccnz .LBB0_709
	s_waitcnt vmcnt(0)
	s_waitcnt vmcnt(0) lgkmcnt(0)
	s_barrier
	s_mov_b64 s[74:75], exec
	v_readlane_b32 s0, v254, 2
	v_readlane_b32 s1, v254, 3
	s_and_b64 s[0:1], s[74:75], s[0:1]
	s_mov_b64 exec, s[0:1]
	s_cbranch_execz .LBB0_708
	s_add_u32 s4, s78, 0x12f40
	s_addc_u32 s5, s79, 0
	v_mov_b32_e32 v0, 0
	v_mov_b32_e32 v1, 1
	global_atomic_add v0, v1, s[4:5]
	s_cmp_lg_u32 s88, 0x100
	s_cbranch_scc1 .Lgb3_orig
	v_mov_b32_e32 v2, 0x23fc8
	ds_read_b32 v2, v2
	s_and_b32 s0, s70, 7
	s_lshl_b32 s0, s0, 8
	s_add_i32 s0, s0, 0x12400
	s_add_u32 s4, s78, s0
	s_addc_u32 s5, s79, 0
	s_lshr_b32 s6, s88, 3
	v_mov_b32_e32 v0, 0
	v_mov_b32_e32 v1, 1
	s_waitcnt vmcnt(0) lgkmcnt(0)
	v_readfirstlane_b32 s9, v2
	s_cmp_eq_u32 s9, 1
	s_cbranch_scc1 .Lgb3_norel
	buffer_wbl2 sc1
	s_waitcnt vmcnt(0)
.Lgb3_norel:
	global_atomic_add v2, v0, v1, s[4:5] sc0
	s_waitcnt vmcnt(0)
	v_readfirstlane_b32 s7, v2
	s_add_i32 s7, s7, 1
	s_cmp_lt_u32 s7, s6
	s_cbranch_scc1 .Lgb3_spin
	s_cmp_eq_u32 s9, 1
	s_cbranch_scc0 .Lgb3_fl
	buffer_wbl2 sc1
	s_waitcnt vmcnt(0)
.Lgb3_fl:
	s_add_u32 s4, s78, 0x12c00
	s_addc_u32 s5, s79, 0
	global_atomic_add v0, v1, s[4:5]
	s_branch .Lgb3_acq

; #define LAS __attribute__((address_space(3)))
; __device__ __forceinline__ unsigned xb_ld(unsigned* p) { return __hip_atomic_load(p, __ATOMIC_RELAXED, __HIP_MEMORY_SCOPE_AGENT); }
; __device__ __forceinline__ unsigned xb_add(unsigned* p, unsigned v) { return __hip_atomic_fetch_add(p, v, __ATOMIC_RELAXED, __HIP_MEMORY_SCOPE_AGENT); }
; __device__ __forceinline__ unsigned xb_xcc_id() { return (unsigned)__builtin_amdgcn_s_getreg((3 << 11) | 20) & 0xFu; }
; #define SEAM(k) do { if (IN(k) && IN((k) + 1)) { grid_barrier(barw, (k), bst); } } while (0)
; __device__ __forceinline__ void grid_barrier(unsigned* barw, int k, volatile LAS unsigned* st) {
;     asm volatile("s_waitcnt vmcnt(0)" ::: "memory");
;     __syncthreads();
;     if (threadIdx.x == 0) {
;         __builtin_amdgcn_s_waitcnt(0);
;         const unsigned x = xb_xcc_id();
;         unsigned nloc = st[0], nx = st[1];
;         if (nloc == 0u) {
;             const unsigned G = gridDim.x;
;             for (;;) { unsigned sum = 0u, cnt = 0u, mine = 0u;
; #pragma unroll
;                 for (unsigned j = 0; j < 16; ++j) { const unsigned c = xb_ld(barw + 64 * j); sum += c; cnt += (c > 0u) ? 1u : 0u; mine = (j == x) ? c : mine; }
;                 if (sum == G) { nloc = mine; nx = cnt; break; }
;                 __builtin_amdgcn_s_sleep(1); }
;             st[0] = nloc; st[1] = nx;
;         }
;         unsigned* sb = barw + 1024 + k * 2304;
;         const unsigned old = xb_add(sb + 64 * x, 1u);
;         if (old + 1u == nloc) {
;             __builtin_amdgcn_fence(__ATOMIC_RELEASE, "agent");
;             asm volatile("s_waitcnt vmcnt(0)" ::: "memory");
;             const unsigned og = xb_add(sb + 2048, 1u);
;             if (og + 1u == nx) xb_add(sb + 2112, 1u);
;             else while (xb_ld(sb + 2112) == 0u) __builtin_amdgcn_s_sleep(1);
;             __builtin_amdgcn_fence(__ATOMIC_ACQUIRE, "agent");
;             xb_add(sb + 1024 + 64 * x, 1u);
;             asm volatile("s_waitcnt vmcnt(0)" ::: "memory");
;         } else {
;             while (xb_ld(sb + 1024 + 64 * x) == 0u) __builtin_amdgcn_s_sleep(1);
;             __builtin_amdgcn_fence(__ATOMIC_ACQUIRE, "agent");
;             asm volatile("s_waitcnt vmcnt(0)" ::: "memory");
;         }
;     }
;     __syncthreads();
; __global__ void __launch_bounds__(NWAVES * 64, 2) fwd_kernel(Args args) {
;     ...
;     SEAM(4);
.LBB0_886:
	v_readlane_b32 s0, v254, 0
	v_readlane_b32 s1, v254, 1
	s_cmp_gt_i32 s1, 5
	s_cselect_b64 s[72:73], -1, 0
	s_and_b64 s[0:1], s[28:29], s[72:73]
	s_andn2_b64 vcc, exec, s[0:1]
	s_cbranch_vccnz .LBB0_915
	s_waitcnt vmcnt(0)
	s_waitcnt vmcnt(0) lgkmcnt(0)
	s_barrier
	s_mov_b64 s[74:75], exec
	v_readlane_b32 s0, v254, 2
	v_readlane_b32 s1, v254, 3
	s_and_b64 s[0:1], s[74:75], s[0:1]
	s_mov_b64 exec, s[0:1]
	s_cbranch_execz .LBB0_914
	s_cmp_lg_u32 s88, 0x100
	s_cbranch_scc1 .Lgb2_orig
	v_mov_b32_e32 v2, 0x23fc8
	ds_read_b32 v2, v2
	s_and_b32 s0, s70, 7
	s_lshl_b32 s0, s0, 8
	s_add_i32 s0, s0, 0x11c00
	s_add_u32 s4, s78, s0
	s_addc_u32 s5, s79, 0
	s_lshr_b32 s6, s88, 3
	v_mov_b32_e32 v0, 0
	v_mov_b32_e32 v1, 1
	s_waitcnt vmcnt(0) lgkmcnt(0)
	v_readfirstlane_b32 s9, v2
	s_cmp_eq_u32 s9, 1
	s_cbranch_scc1 .Lgb2_norel
	buffer_wbl2 sc1
	s_waitcnt vmcnt(0)
.Lgb2_norel:
	global_atomic_add v0, v1, s[4:5]
.Lgb2_spin:
	global_load_dword v2, v0, s[4:5] sc1
	s_waitcnt vmcnt(0)
	v_readfirstlane_b32 s7, v2
	s_cmp_ge_u32 s7, s6
	s_cbranch_scc1 .Lgb2_acq
	s_sleep 1
	s_branch .Lgb2_spin
.Lgb2_acq:
	s_add_u32 s4, s78, 0x12c00
	s_addc_u32 s5, s79, 0

; #define LAS __attribute__((address_space(3)))
; __device__ __forceinline__ unsigned xb_ld(unsigned* p) { return __hip_atomic_load(p, __ATOMIC_RELAXED, __HIP_MEMORY_SCOPE_AGENT); }
; __device__ __forceinline__ unsigned xb_add(unsigned* p, unsigned v) { return __hip_atomic_fetch_add(p, v, __ATOMIC_RELAXED, __HIP_MEMORY_SCOPE_AGENT); }
; __device__ __forceinline__ unsigned xb_xcc_id() { return (unsigned)__builtin_amdgcn_s_getreg((3 << 11) | 20) & 0xFu; }
; #define SEAM(k) do { if (IN(k) && IN((k) + 1)) { grid_barrier(barw, (k), bst); } } while (0)
; __device__ __forceinline__ void grid_barrier(unsigned* barw, int k, volatile LAS unsigned* st) {
;     asm volatile("s_waitcnt vmcnt(0)" ::: "memory");
;     __syncthreads();
;     if (threadIdx.x == 0) {
;         __builtin_amdgcn_s_waitcnt(0);
;         const unsigned x = xb_xcc_id();
;         unsigned nloc = st[0], nx = st[1];
;         if (nloc == 0u) {
;             const unsigned G = gridDim.x;
;             for (;;) { unsigned sum = 0u, cnt = 0u, mine = 0u;
; #pragma unroll
;                 for (unsigned j = 0; j < 16; ++j) { const unsigned c = xb_ld(barw + 64 * j); sum += c; cnt += (c > 0u) ? 1u : 0u; mine = (j == x) ? c : mine; }
;                 if (sum == G) { nloc = mine; nx = cnt; break; }
;                 __builtin_amdgcn_s_sleep(1); }
;             st[0] = nloc; st[1] = nx;
;         }
;         unsigned* sb = barw + 1024 + k * 2304;
;         const unsigned old = xb_add(sb + 64 * x, 1u);
;         if (old + 1u == nloc) {
;             __builtin_amdgcn_fence(__ATOMIC_RELEASE, "agent");
;             asm volatile("s_waitcnt vmcnt(0)" ::: "memory");
;             const unsigned og = xb_add(sb + 2048, 1u);
;             if (og + 1u == nx) xb_add(sb + 2112, 1u);
;             else while (xb_ld(sb + 2112) == 0u) __builtin_amdgcn_s_sleep(1);
;             __builtin_amdgcn_fence(__ATOMIC_ACQUIRE, "agent");
;             xb_add(sb + 1024 + 64 * x, 1u);
;             asm volatile("s_waitcnt vmcnt(0)" ::: "memory");
;         } else {
;             while (xb_ld(sb + 1024 + 64 * x) == 0u) __builtin_amdgcn_s_sleep(1);
;             __builtin_amdgcn_fence(__ATOMIC_ACQUIRE, "agent");
;             asm volatile("s_waitcnt vmcnt(0)" ::: "memory");
;         }
;     }
;     __syncthreads();
; __global__ void __launch_bounds__(NWAVES * 64, 2) fwd_kernel(Args args) {
;     ...
;     SEAM(5);
.LBB0_960:
	v_readlane_b32 s2, v254, 0
	v_readlane_b32 s3, v254, 1
	s_cmp_gt_i32 s3, 6
	s_cselect_b64 s[72:73], -1, 0
	s_and_b64 s[0:1], s[0:1], s[72:73]
	s_andn2_b64 vcc, exec, s[0:1]
	s_cbranch_vccnz .LBB0_989
	s_waitcnt vmcnt(0)
	s_waitcnt vmcnt(0) lgkmcnt(0)
	s_barrier
	s_mov_b64 s[74:75], exec
	v_readlane_b32 s0, v254, 2
	v_readlane_b32 s1, v254, 3
	s_and_b64 s[0:1], s[74:75], s[0:1]
	s_mov_b64 exec, s[0:1]
	s_cbranch_execz .LBB0_988
	s_add_u32 s4, s78, 0x12f00
	s_addc_u32 s5, s79, 0
	v_mov_b32_e32 v0, 0
	v_mov_b32_e32 v1, 1
	global_atomic_add v0, v1, s[4:5]
	s_and_b32 s0, s88, 7
	s_cmp_lg_u32 s0, 0
	s_cbranch_scc1 .Lgb0_orig
	v_mov_b32_e32 v2, 0x23fc8
	ds_read_b32 v2, v2
	s_and_b32 s0, s70, 7
	s_lshl_b32 s0, s0, 8
	s_add_i32 s0, s0, 0x10c00
	s_add_u32 s4, s78, s0
	s_addc_u32 s5, s79, 0
	s_lshr_b32 s6, s88, 3
	v_mov_b32_e32 v0, 0
	v_mov_b32_e32 v1, 1
	s_waitcnt vmcnt(0) lgkmcnt(0)
	v_readfirstlane_b32 s9, v2
	s_cmp_eq_u32 s9, 1
	s_cbranch_scc1 .Lgb0_norel
	buffer_wbl2 sc1
	s_waitcnt vmcnt(0)

; #define LAS __attribute__((address_space(3)))
; __device__ __forceinline__ unsigned xb_ld(unsigned* p) { return __hip_atomic_load(p, __ATOMIC_RELAXED, __HIP_MEMORY_SCOPE_AGENT); }
; __device__ __forceinline__ unsigned xb_add(unsigned* p, unsigned v) { return __hip_atomic_fetch_add(p, v, __ATOMIC_RELAXED, __HIP_MEMORY_SCOPE_AGENT); }
; __device__ __forceinline__ unsigned xb_xcc_id() { return (unsigned)__builtin_amdgcn_s_getreg((3 << 11) | 20) & 0xFu; }
; #define SEAM(k) do { if (IN(k) && IN((k) + 1)) { grid_barrier(barw, (k), bst); } } while (0)
; __device__ __forceinline__ void grid_barrier(unsigned* barw, int k, volatile LAS unsigned* st) {
;     asm volatile("s_waitcnt vmcnt(0)" ::: "memory");
;     __syncthreads();
;     if (threadIdx.x == 0) {
;         __builtin_amdgcn_s_waitcnt(0);
;         const unsigned x = xb_xcc_id();
;         unsigned nloc = st[0], nx = st[1];
;         if (nloc == 0u) {
;             const unsigned G = gridDim.x;
;             for (;;) { unsigned sum = 0u, cnt = 0u, mine = 0u;
; #pragma unroll
;                 for (unsigned j = 0; j < 16; ++j) { const unsigned c = xb_ld(barw + 64 * j); sum += c; cnt += (c > 0u) ? 1u : 0u; mine = (j == x) ? c : mine; }
;                 if (sum == G) { nloc = mine; nx = cnt; break; }
;                 __builtin_amdgcn_s_sleep(1); }
;             st[0] = nloc; st[1] = nx;
;         }
;         unsigned* sb = barw + 1024 + k * 2304;
;         const unsigned old = xb_add(sb + 64 * x, 1u);
;         if (old + 1u == nloc) {
;             __builtin_amdgcn_fence(__ATOMIC_RELEASE, "agent");
;             asm volatile("s_waitcnt vmcnt(0)" ::: "memory");
;             const unsigned og = xb_add(sb + 2048, 1u);
;             if (og + 1u == nx) xb_add(sb + 2112, 1u);
;             else while (xb_ld(sb + 2112) == 0u) __builtin_amdgcn_s_sleep(1);
;             __builtin_amdgcn_fence(__ATOMIC_ACQUIRE, "agent");
;             xb_add(sb + 1024 + 64 * x, 1u);
;             asm volatile("s_waitcnt vmcnt(0)" ::: "memory");
;         } else {
;             while (xb_ld(sb + 1024 + 64 * x) == 0u) __builtin_amdgcn_s_sleep(1);
;             __builtin_amdgcn_fence(__ATOMIC_ACQUIRE, "agent");
;             asm volatile("s_waitcnt vmcnt(0)" ::: "memory");
;         }
;     }
;     __syncthreads();
; __global__ void __launch_bounds__(NWAVES * 64, 2) fwd_kernel(Args args) {
;     ...
;     SEAM(6);
.LBB0_1014:
	v_readlane_b32 s2, v254, 0
	v_readlane_b32 s3, v254, 1
	s_cmp_gt_i32 s3, 7
	s_cselect_b64 s[68:69], -1, 0
	s_and_b64 s[0:1], s[0:1], s[68:69]
	s_andn2_b64 vcc, exec, s[0:1]
	s_cbranch_vccnz .LBB0_1043
	s_waitcnt vmcnt(0)
	s_waitcnt vmcnt(0) lgkmcnt(0)
	s_barrier
	s_mov_b64 s[72:73], exec
	v_readlane_b32 s0, v254, 2
	v_readlane_b32 s1, v254, 3
	s_and_b64 s[0:1], s[72:73], s[0:1]
	s_mov_b64 exec, s[0:1]
	s_cbranch_execz .LBB0_1042
	s_and_b32 s0, s88, 7
	s_cmp_lg_u32 s0, 0
	s_cbranch_scc1 .Lgb1_orig
	v_mov_b32_e32 v2, 0x23fc8
	ds_read_b32 v2, v2
	s_and_b32 s0, s70, 7
	s_lshl_b32 s0, s0, 8
	s_add_i32 s0, s0, 0x11400
	s_add_u32 s4, s78, s0
	s_addc_u32 s5, s79, 0
	s_lshr_b32 s6, s88, 3
	v_mov_b32_e32 v0, 0
	v_mov_b32_e32 v1, 1
	s_waitcnt vmcnt(0) lgkmcnt(0)
	v_readfirstlane_b32 s9, v2
	s_cmp_eq_u32 s9, 1
	s_cbranch_scc1 .Lgb1_norel
	buffer_wbl2 sc1
	s_waitcnt vmcnt(0)
